# attention score waves: key-half 0 softmax computed speculatively (current running max) inside the gaps of the key-half 1 QK MFMAs; slow path recomputes when the max must rise
# baseline (speedup 1.0000x reference)
.LBB0_407:
.LBB0_409:
	s_cmp_ge_i32 s8, s27
	s_cbranch_scc1 .LBB0_413
	s_mul_hi_u32 s8, s8, 0xaaaaaaab
	s_lshr_b32 s8, s8, 1
	s_mul_i32 s8, s8, 0xfffe1400
	s_add_i32 s8, s28, s8
	v_add_u32_e32 v175, s8, v174
	ds_read_b128 v[176:179], v175
	ds_read_b128 v[180:183], v175 offset:32
	ds_read_b128 v[184:187], v175 offset:64
	ds_read_b128 v[188:191], v175 offset:96
	ds_read_b128 v[220:223], v175 offset:128
	ds_read_b128 v[224:227], v175 offset:160
	ds_read_b128 v[228:231], v175 offset:192
	ds_read_b128 v[232:235], v175 offset:224
	ds_read_b128 v[236:239], v175 offset:256
	ds_read_b128 v[240:243], v175 offset:288
	s_waitcnt vmcnt(19) lgkmcnt(9)
	v_mfma_f32_32x32x16_bf16 v[18:33], v[176:179], v[34:37], 0
	ds_read_b128 v[176:179], v175 offset:320
	s_waitcnt vmcnt(18) lgkmcnt(9)
	v_mfma_f32_32x32x16_bf16 v[18:33], v[180:183], v[38:41], v[18:33]
	ds_read_b128 v[180:183], v175 offset:352
	s_waitcnt vmcnt(17) lgkmcnt(9)
	v_mfma_f32_32x32x16_bf16 v[18:33], v[184:187], v[42:45], v[18:33]
	ds_read_b128 v[184:187], v175 offset:384
	s_waitcnt vmcnt(16) lgkmcnt(9)
	v_mfma_f32_32x32x16_bf16 v[18:33], v[188:191], v[46:49], v[18:33]
	ds_read_b128 v[188:191], v175 offset:416
	s_waitcnt vmcnt(15) lgkmcnt(9)
	v_mfma_f32_32x32x16_bf16 v[18:33], v[220:223], v[50:53], v[18:33]
	ds_read_b128 v[220:223], v175 offset:448
	s_waitcnt vmcnt(14) lgkmcnt(9)
	v_mfma_f32_32x32x16_bf16 v[18:33], v[224:227], v[54:57], v[18:33]
	ds_read_b128 v[224:227], v175 offset:480
	s_waitcnt vmcnt(13) lgkmcnt(9)
	v_mfma_f32_32x32x16_bf16 v[18:33], v[228:231], v[58:61], v[18:33]
	ds_read_b128 v[228:231], v175 offset:512
	s_waitcnt vmcnt(12) lgkmcnt(9)
	v_mfma_f32_32x32x16_bf16 v[18:33], v[232:235], v[62:65], v[18:33]
	ds_read_b128 v[232:235], v175 offset:544
	s_waitcnt vmcnt(11) lgkmcnt(9)
	v_mfma_f32_32x32x16_bf16 v[18:33], v[236:239], v[66:69], v[18:33]
	ds_read_b128 v[236:239], v175 offset:576
	s_waitcnt vmcnt(10) lgkmcnt(9)
	v_mfma_f32_32x32x16_bf16 v[18:33], v[240:243], v[70:73], v[18:33]
	ds_read_b128 v[240:243], v175 offset:608
	s_waitcnt vmcnt(9) lgkmcnt(9)
	v_mfma_f32_32x32x16_bf16 v[18:33], v[176:179], v[74:77], v[18:33]
	ds_read_b128 v[176:179], v175 offset:20992
	s_waitcnt vmcnt(8) lgkmcnt(9)
	v_mfma_f32_32x32x16_bf16 v[18:33], v[180:183], v[78:81], v[18:33]
	ds_read_b128 v[180:183], v175 offset:21024
	s_waitcnt vmcnt(7) lgkmcnt(9)
	v_mfma_f32_32x32x16_bf16 v[18:33], v[184:187], v[82:85], v[18:33]
	ds_read_b128 v[184:187], v175 offset:21056
	s_waitcnt vmcnt(6) lgkmcnt(9)
	v_mfma_f32_32x32x16_bf16 v[18:33], v[188:191], v[86:89], v[18:33]
	ds_read_b128 v[188:191], v175 offset:21088
	s_waitcnt vmcnt(5) lgkmcnt(9)
	v_mfma_f32_32x32x16_bf16 v[18:33], v[220:223], v[90:93], v[18:33]
	ds_read_b128 v[220:223], v175 offset:21120
	s_waitcnt vmcnt(4) lgkmcnt(9)
	v_mfma_f32_32x32x16_bf16 v[18:33], v[224:227], v[94:97], v[18:33]
	ds_read_b128 v[224:227], v175 offset:21152
	s_waitcnt vmcnt(3) lgkmcnt(9)
	v_mfma_f32_32x32x16_bf16 v[18:33], v[228:231], v[98:101], v[18:33]
	ds_read_b128 v[228:231], v175 offset:21184
	s_waitcnt vmcnt(2) lgkmcnt(9)
	v_mfma_f32_32x32x16_bf16 v[18:33], v[232:235], v[102:105], v[18:33]
	ds_read_b128 v[232:235], v175 offset:21216
	s_waitcnt vmcnt(1) lgkmcnt(9)
	v_mfma_f32_32x32x16_bf16 v[18:33], v[236:239], v[106:109], v[18:33]
	ds_read_b128 v[236:239], v175 offset:21248
	s_waitcnt vmcnt(0) lgkmcnt(9)
	v_mfma_f32_32x32x16_bf16 v[18:33], v[240:243], v[110:113], v[18:33]
	ds_read_b128 v[240:243], v175 offset:21280
	s_waitcnt lgkmcnt(9)
	v_mfma_f32_32x32x16_bf16 v[2:17], v[176:179], v[34:37], 0
	ds_read_b128 v[176:179], v175 offset:21312
	s_waitcnt lgkmcnt(9)
	v_mfma_f32_32x32x16_bf16 v[2:17], v[180:183], v[38:41], v[2:17]
	ds_read_b128 v[180:183], v175 offset:21344
	s_waitcnt lgkmcnt(9)
	v_mfma_f32_32x32x16_bf16 v[2:17], v[184:187], v[42:45], v[2:17]
	ds_read_b128 v[184:187], v175 offset:21376
	s_waitcnt lgkmcnt(9)
	v_mfma_f32_32x32x16_bf16 v[2:17], v[188:191], v[46:49], v[2:17]
	ds_read_b128 v[188:191], v175 offset:21408
	s_waitcnt lgkmcnt(9)
	v_mfma_f32_32x32x16_bf16 v[2:17], v[220:223], v[50:53], v[2:17]
	ds_read_b128 v[220:223], v175 offset:21440
	v_max3_f32 v130, v18, v19, v20
	v_max3_f32 v130, v130, v21, v22
	v_max3_f32 v130, v130, v23, v24
	v_max3_f32 v130, v130, v25, v26
	s_waitcnt lgkmcnt(9)
	v_mfma_f32_32x32x16_bf16 v[2:17], v[224:227], v[54:57], v[2:17]
	ds_read_b128 v[224:227], v175 offset:21472
	v_max3_f32 v130, v130, v27, v28
	v_max3_f32 v130, v130, v29, v30
	v_max3_f32 v130, v130, v31, v32
	v_max_f32_e32 v130, v130, v33
	s_waitcnt lgkmcnt(9)
	v_mfma_f32_32x32x16_bf16 v[2:17], v[228:231], v[58:61], v[2:17]
	ds_read_b128 v[228:231], v175 offset:21504
	v_sub_f32_e32 v114, v18, v165
	v_exp_f32_e32 v114, v114
	v_sub_f32_e32 v115, v19, v165
	v_exp_f32_e32 v115, v115
	s_waitcnt lgkmcnt(9)
	v_mfma_f32_32x32x16_bf16 v[2:17], v[232:235], v[62:65], v[2:17]
	ds_read_b128 v[232:235], v175 offset:21536
	v_sub_f32_e32 v116, v20, v165
	v_exp_f32_e32 v116, v116
	v_sub_f32_e32 v117, v21, v165
	v_exp_f32_e32 v117, v117
	s_waitcnt lgkmcnt(9)
	v_mfma_f32_32x32x16_bf16 v[2:17], v[236:239], v[66:69], v[2:17]
	ds_read_b128 v[236:239], v175 offset:21568
	v_sub_f32_e32 v118, v22, v165
	v_exp_f32_e32 v118, v118
	v_sub_f32_e32 v119, v23, v165
	v_exp_f32_e32 v119, v119
	s_waitcnt lgkmcnt(9)
	v_mfma_f32_32x32x16_bf16 v[2:17], v[240:243], v[70:73], v[2:17]
	ds_read_b128 v[240:243], v175 offset:21600
	v_sub_f32_e32 v120, v24, v165
	v_exp_f32_e32 v120, v120
	v_sub_f32_e32 v121, v25, v165
	v_exp_f32_e32 v121, v121
	s_waitcnt lgkmcnt(9)
	v_mfma_f32_32x32x16_bf16 v[2:17], v[176:179], v[74:77], v[2:17]
	v_sub_f32_e32 v122, v26, v165
	v_exp_f32_e32 v122, v122
	v_sub_f32_e32 v123, v27, v165
	v_exp_f32_e32 v123, v123
	s_waitcnt lgkmcnt(8)
	v_mfma_f32_32x32x16_bf16 v[2:17], v[180:183], v[78:81], v[2:17]
	v_sub_f32_e32 v124, v28, v165
	v_exp_f32_e32 v124, v124
	v_sub_f32_e32 v125, v29, v165
	v_exp_f32_e32 v125, v125
	s_waitcnt lgkmcnt(7)
	v_mfma_f32_32x32x16_bf16 v[2:17], v[184:187], v[82:85], v[2:17]
	v_sub_f32_e32 v126, v30, v165
	v_exp_f32_e32 v126, v126
	v_sub_f32_e32 v127, v31, v165
	v_exp_f32_e32 v127, v127
	s_waitcnt lgkmcnt(6)
	v_mfma_f32_32x32x16_bf16 v[2:17], v[188:191], v[86:89], v[2:17]
	v_sub_f32_e32 v128, v32, v165
	v_exp_f32_e32 v128, v128
	v_sub_f32_e32 v129, v33, v165
	v_exp_f32_e32 v129, v129
	s_waitcnt lgkmcnt(5)
	v_mfma_f32_32x32x16_bf16 v[2:17], v[220:223], v[90:93], v[2:17]
	v_add_f32_e32 v131, v114, v115
	v_add_f32_e32 v131, v131, v116
	v_add_f32_e32 v131, v131, v117
	v_add_f32_e32 v131, v131, v118
	s_waitcnt lgkmcnt(4)
	v_mfma_f32_32x32x16_bf16 v[2:17], v[224:227], v[94:97], v[2:17]
	v_add_f32_e32 v131, v131, v119
	v_add_f32_e32 v131, v131, v120
	v_add_f32_e32 v131, v131, v121
	v_add_f32_e32 v131, v131, v122
	s_waitcnt lgkmcnt(3)
	v_mfma_f32_32x32x16_bf16 v[2:17], v[228:231], v[98:101], v[2:17]
	v_add_f32_e32 v131, v131, v123
	v_add_f32_e32 v131, v131, v124
	v_add_f32_e32 v131, v131, v125
	v_add_f32_e32 v131, v131, v126
	s_waitcnt lgkmcnt(2)
	v_mfma_f32_32x32x16_bf16 v[2:17], v[232:235], v[102:105], v[2:17]
	v_add_f32_e32 v131, v131, v127
	v_add_f32_e32 v131, v131, v128
	v_add_f32_e32 v131, v131, v129
	v_cvt_pk_bf16_f32 v132, v114, v115
	s_waitcnt lgkmcnt(1)
	v_mfma_f32_32x32x16_bf16 v[2:17], v[236:239], v[106:109], v[2:17]
	s_waitcnt lgkmcnt(0)
	v_mfma_f32_32x32x16_bf16 v[2:17], v[240:243], v[110:113], v[2:17]
	v_cvt_pk_bf16_f32 v133, v116, v117
	v_cvt_pk_bf16_f32 v134, v118, v119
	v_cvt_pk_bf16_f32 v135, v120, v121
	v_cvt_pk_bf16_f32 v136, v122, v123
	v_cvt_pk_bf16_f32 v137, v124, v125
	v_cvt_pk_bf16_f32 v138, v126, v127
	v_cvt_pk_bf16_f32 v139, v128, v129
	s_and_b32 s8, s29, 4
	s_or_b32 s8, s8, s91
	s_mulk_i32 s8, 0x1080
	s_add_i32 s8, s8, 0x1ec00
	v_add_u32_e32 v140, s8, v169
	ds_write_b128 v140, v[132:135]
	ds_write_b128 v140, v[136:139] offset:1024
	v_max3_f32 v141, v2, v3, v4
	v_max3_f32 v141, v141, v5, v6
	v_max3_f32 v141, v141, v7, v8
	v_max3_f32 v141, v141, v9, v10
	v_max3_f32 v141, v141, v11, v12
	v_max3_f32 v141, v141, v13, v14
	v_max3_f32 v141, v141, v15, v16
	v_max_f32_e32 v141, v141, v17
	v_max_f32_e32 v141, v141, v130
	v_mov_b32_e32 v142, v141
	s_nop 1
	v_permlane32_swap_b32_e32 v142, v141
	v_max_f32_e32 v141, v141, v142
	v_sub_f32_e32 v142, v141, v165
	v_cmp_lt_f32_e32 vcc, 8.0, v142
	s_cbranch_vccnz .Lsc_slow
	v_sub_f32_e32 v2, v2, v165
	v_exp_f32_e32 v2, v2
	v_sub_f32_e32 v3, v3, v165
	v_exp_f32_e32 v3, v3
	v_sub_f32_e32 v4, v4, v165
	v_exp_f32_e32 v4, v4
	v_sub_f32_e32 v5, v5, v165
	v_exp_f32_e32 v5, v5
	v_sub_f32_e32 v6, v6, v165
	v_exp_f32_e32 v6, v6
	v_sub_f32_e32 v7, v7, v165
	v_exp_f32_e32 v7, v7
	v_sub_f32_e32 v8, v8, v165
	v_exp_f32_e32 v8, v8
	v_sub_f32_e32 v9, v9, v165
	v_exp_f32_e32 v9, v9
	v_sub_f32_e32 v10, v10, v165
	v_exp_f32_e32 v10, v10
	v_sub_f32_e32 v11, v11, v165
	v_exp_f32_e32 v11, v11
	v_sub_f32_e32 v12, v12, v165
	v_exp_f32_e32 v12, v12
	v_sub_f32_e32 v13, v13, v165
	v_exp_f32_e32 v13, v13
	v_sub_f32_e32 v14, v14, v165
	v_exp_f32_e32 v14, v14
	v_sub_f32_e32 v15, v15, v165
	v_exp_f32_e32 v15, v15
	v_sub_f32_e32 v16, v16, v165
	v_exp_f32_e32 v16, v16
	v_sub_f32_e32 v17, v17, v165
	v_exp_f32_e32 v17, v17
	v_add_f32_e32 v131, v131, v2
	v_add_f32_e32 v131, v131, v3
	v_add_f32_e32 v131, v131, v4
	v_add_f32_e32 v131, v131, v5
	v_add_f32_e32 v131, v131, v6
	v_add_f32_e32 v131, v131, v7
	v_add_f32_e32 v131, v131, v8
	v_add_f32_e32 v131, v131, v9
	v_add_f32_e32 v131, v131, v10
	v_add_f32_e32 v131, v131, v11
	v_add_f32_e32 v131, v131, v12
	v_add_f32_e32 v131, v131, v13
	v_add_f32_e32 v131, v131, v14
	v_add_f32_e32 v131, v131, v15
	v_add_f32_e32 v131, v131, v16
	v_add_f32_e32 v131, v131, v17
	v_mov_b32_e32 v142, v131
	s_nop 1
	v_permlane32_swap_b32_e32 v142, v131
	v_add_f32_e32 v131, v131, v142
	v_cvt_pk_bf16_f32 v132, v2, v3
	v_cvt_pk_bf16_f32 v133, v4, v5
	v_cvt_pk_bf16_f32 v134, v6, v7
	v_cvt_pk_bf16_f32 v135, v8, v9
	v_cvt_pk_bf16_f32 v136, v10, v11
	v_cvt_pk_bf16_f32 v137, v12, v13
	v_cvt_pk_bf16_f32 v138, v14, v15
	v_cvt_pk_bf16_f32 v139, v16, v17
	ds_write_b128 v140, v[132:135] offset:2048
	ds_write_b128 v140, v[136:139] offset:3072
	v_mov_b32_e32 v144, 1.0
	s_and_saveexec_b64 s[16:17], s[4:5]
	v_add_u32_e32 v143, s8, v171
	ds_write_b32 v143, v144 offset:4096
	s_or_b64 exec, exec, s[16:17]
	v_add_f32_e32 v0, v0, v131
	v_mov_b32_e32 v175, v165
	s_branch .LBB0_414
.Lsc_slow:
	v_max_f32_e32 v175, v165, v141
	v_sub_f32_e32 v144, v165, v175
	v_exp_f32_e32 v144, v144
	v_sub_f32_e32 v114, v18, v175
	v_exp_f32_e32 v114, v114
	v_sub_f32_e32 v115, v19, v175
	v_exp_f32_e32 v115, v115
	v_sub_f32_e32 v116, v20, v175
	v_exp_f32_e32 v116, v116
	v_sub_f32_e32 v117, v21, v175
	v_exp_f32_e32 v117, v117
	v_sub_f32_e32 v118, v22, v175
	v_exp_f32_e32 v118, v118
	v_sub_f32_e32 v119, v23, v175
	v_exp_f32_e32 v119, v119
	v_sub_f32_e32 v120, v24, v175
	v_exp_f32_e32 v120, v120
	v_sub_f32_e32 v121, v25, v175
	v_exp_f32_e32 v121, v121
	v_sub_f32_e32 v122, v26, v175
	v_exp_f32_e32 v122, v122
	v_sub_f32_e32 v123, v27, v175
	v_exp_f32_e32 v123, v123
	v_sub_f32_e32 v124, v28, v175
	v_exp_f32_e32 v124, v124
	v_sub_f32_e32 v125, v29, v175
	v_exp_f32_e32 v125, v125
	v_sub_f32_e32 v126, v30, v175
	v_exp_f32_e32 v126, v126
	v_sub_f32_e32 v127, v31, v175
	v_exp_f32_e32 v127, v127
	v_sub_f32_e32 v128, v32, v175
	v_exp_f32_e32 v128, v128
	v_sub_f32_e32 v129, v33, v175
	v_exp_f32_e32 v129, v129
	v_sub_f32_e32 v2, v2, v175
	v_exp_f32_e32 v2, v2
	v_sub_f32_e32 v3, v3, v175
	v_exp_f32_e32 v3, v3
	v_sub_f32_e32 v4, v4, v175
	v_exp_f32_e32 v4, v4
	v_sub_f32_e32 v5, v5, v175
	v_exp_f32_e32 v5, v5
	v_sub_f32_e32 v6, v6, v175
	v_exp_f32_e32 v6, v6
	v_sub_f32_e32 v7, v7, v175
	v_exp_f32_e32 v7, v7
	v_sub_f32_e32 v8, v8, v175
	v_exp_f32_e32 v8, v8
	v_sub_f32_e32 v9, v9, v175
	v_exp_f32_e32 v9, v9
	v_sub_f32_e32 v10, v10, v175
	v_exp_f32_e32 v10, v10
	v_sub_f32_e32 v11, v11, v175
	v_exp_f32_e32 v11, v11
	v_sub_f32_e32 v12, v12, v175
	v_exp_f32_e32 v12, v12
	v_sub_f32_e32 v13, v13, v175
	v_exp_f32_e32 v13, v13
	v_sub_f32_e32 v14, v14, v175
	v_exp_f32_e32 v14, v14
	v_sub_f32_e32 v15, v15, v175
	v_exp_f32_e32 v15, v15
	v_sub_f32_e32 v16, v16, v175
	v_exp_f32_e32 v16, v16
	v_sub_f32_e32 v17, v17, v175
	v_exp_f32_e32 v17, v17
	v_add_f32_e32 v131, v114, v115
	v_add_f32_e32 v131, v131, v116
	v_add_f32_e32 v131, v131, v117
	v_add_f32_e32 v131, v131, v118
	v_add_f32_e32 v131, v131, v119
	v_add_f32_e32 v131, v131, v120
	v_add_f32_e32 v131, v131, v121
	v_add_f32_e32 v131, v131, v122
	v_add_f32_e32 v131, v131, v123
	v_add_f32_e32 v131, v131, v124
	v_add_f32_e32 v131, v131, v125
	v_add_f32_e32 v131, v131, v126
	v_add_f32_e32 v131, v131, v127
	v_add_f32_e32 v131, v131, v128
	v_add_f32_e32 v131, v131, v129
	v_add_f32_e32 v131, v131, v2
	v_add_f32_e32 v131, v131, v3
	v_add_f32_e32 v131, v131, v4
	v_add_f32_e32 v131, v131, v5
	v_add_f32_e32 v131, v131, v6
	v_add_f32_e32 v131, v131, v7
	v_add_f32_e32 v131, v131, v8
	v_add_f32_e32 v131, v131, v9
	v_add_f32_e32 v131, v131, v10
	v_add_f32_e32 v131, v131, v11
	v_add_f32_e32 v131, v131, v12
	v_add_f32_e32 v131, v131, v13
	v_add_f32_e32 v131, v131, v14
	v_add_f32_e32 v131, v131, v15
	v_add_f32_e32 v131, v131, v16
	v_add_f32_e32 v131, v131, v17
	v_mov_b32_e32 v142, v131
	s_nop 1
	v_permlane32_swap_b32_e32 v142, v131
	v_add_f32_e32 v131, v131, v142
	v_cvt_pk_bf16_f32 v132, v114, v115
	v_cvt_pk_bf16_f32 v133, v116, v117
	v_cvt_pk_bf16_f32 v134, v118, v119
	v_cvt_pk_bf16_f32 v135, v120, v121
	v_cvt_pk_bf16_f32 v136, v122, v123
	v_cvt_pk_bf16_f32 v137, v124, v125
	v_cvt_pk_bf16_f32 v138, v126, v127
	v_cvt_pk_bf16_f32 v139, v128, v129
	ds_write_b128 v140, v[132:135]
	ds_write_b128 v140, v[136:139] offset:1024
	v_cvt_pk_bf16_f32 v132, v2, v3
	v_cvt_pk_bf16_f32 v133, v4, v5
	v_cvt_pk_bf16_f32 v134, v6, v7
	v_cvt_pk_bf16_f32 v135, v8, v9
	v_cvt_pk_bf16_f32 v136, v10, v11
	v_cvt_pk_bf16_f32 v137, v12, v13
	v_cvt_pk_bf16_f32 v138, v14, v15
	v_cvt_pk_bf16_f32 v139, v16, v17
	ds_write_b128 v140, v[132:135] offset:2048
	ds_write_b128 v140, v[136:139] offset:3072
	s_and_saveexec_b64 s[16:17], s[4:5]
	v_add_u32_e32 v143, s8, v171
	ds_write_b32 v143, v144 offset:4096
	s_or_b64 exec, exec, s[16:17]
	v_fmac_f32_e32 v131, v0, v144
	v_mov_b32_e32 v0, v131
	s_branch .LBB0_414
